# v28 + in-proj epilogue reads its 8 per-row rstd values from LDS in one batch
# baseline (speedup 1.0000x reference)
; #define LAS __attribute__((address_space(3)))
; __device__ __forceinline__ u32x4 pack8(const f32x4& v0, const f32x4& v1) { u32x4 w; w.x = cvt_pk_bf16(v0[0], v0[1]); w.y = cvt_pk_bf16(v0[2], v0[3]); w.z = cvt_pk_bf16(v1[0], v1[1]); w.w = cvt_pk_bf16(v1[2], v1[3]); return w; }
; __device__ __forceinline__ float sumsq8(const f32x4& a, const f32x4& b) { return (a[0] * a[0] + a[1] * a[1]) + (a[2] * a[2] + a[3] * a[3]) + (b[0] * b[0] + b[1] * b[1]) + (b[2] * b[2] + b[3] * b[3]); }
;     __device__ __forceinline__ void operator()(const f32x4 (&acc)[2][2][4][2], const Unit& u, int wr, int wc, int fr, int fq) const {
;         const int row0 = u.pm * 256 + wr * 64 + fr, cw = wc * 32 + 8 * fq;
;         unit_rstd<16>(lds, 1.0f / 1024.0f, (wr * 4 + wc) * 64 + fq * 16 + fr);
;         const LAS float* rs = (const LAS float*)(lds + LDS_RS);
; #pragma unroll
;         for (int ai = 0; ai < 2; ++ai)
; #pragma unroll
;             for (int m = 0; m < 4; ++m) {
;                 int row_ = row0 + ai * 128 + m * 16; asm volatile("" : "+v"(row_)); const int row = row_;
;                 const float rstd = rs[wr * 64 + ai * 128 + m * 16 + fr];
;                 f32x4 v[2][2];
; #pragma unroll
;                 for (int bj = 0; bj < 2; ++bj) { v[bj][0] = acc[ai][bj][m][0] * rstd; v[bj][1] = acc[ai][bj][m][1] * rstd; }
;                 if (u.pn < 27) {
;                     bf16_t* dst = P + (size_t)row * LDP + u.pn * 256 + cw;
;                     *(u32x4*)(dst) = pack8(v[0][0], v[0][1]); *(u32x4*)(dst + 128) = pack8(v[1][0], v[1][1]);
;                 } else if (u.pn == 27) {
;                     bf16_t* dst = CQ + (size_t)row * 256 + cw;
;                     *(u32x4*)(dst) = pack8(v[0][0], v[0][1]); *(u32x4*)(dst + 128) = pack8(v[1][0], v[1][1]);
;                     const float s = quad_sum(sumsq8(v[0][0], v[0][1]) + sumsq8(v[1][0], v[1][1]));
;                     if (fq == 0) SSQQ[(size_t)row * 4 + wc] = s;
;                 } else {
;                     *(u32x4*)(CKV + (size_t)row * 128 + cw) = pack8(v[0][0], v[0][1]);
;                     const float s = quad_sum(sumsq8(v[0][0], v[0][1]));
;                     if (fq == 0) SSQKV[(size_t)row * 4 + wc] = s;
.LBB0_274:
	s_or_b64 exec, exec, s[8:9]
	s_lshl_b32 s5, s6, 8
	s_add_i32 s5, s5, s89
	v_or_b32_e32 v171, s5, v147
	v_lshl_add_u32 v172, v147, 2, s95
	v_mov_b32_e32 v152, v171
	v_ashrrev_i32_e32 v149, 4, v18
	s_waitcnt lgkmcnt(0)
	s_barrier
	v_cmp_gt_u32_e64 s[8:9], 16, v18
	ds_read_b32 v18, v172
	ds_read_b32 v232, v172 offset:64
	ds_read_b32 v233, v172 offset:128
	ds_read_b32 v234, v172 offset:192
	ds_read_b32 v235, v172 offset:512
	ds_read_b32 v236, v172 offset:576
	ds_read_b32 v237, v172 offset:640
	ds_read_b32 v238, v172 offset:704
	v_lshlrev_b32_e32 v148, 3, v149
	s_cmp_gt_i32 s4, 26
	v_add_u32_e32 v146, s90, v148
	s_cselect_b64 s[82:83], -1, 0
	s_cmp_lg_u32 s4, 27
	v_lshlrev_b32_e32 v150, 2, v149
	s_cselect_b64 s[84:85], -1, 0
	v_ashrrev_i32_e32 v147, 31, v146
	v_ashrrev_i32_e32 v151, 31, v150
	v_ashrrev_i32_e32 v149, 31, v148
	s_and_b64 s[78:79], s[30:31], s[8:9]
	s_waitcnt lgkmcnt(0)
	v_pk_mul_f32 v[130:131], v[130:131], v[18:19] op_sel_hi:[1,0]
	v_pk_mul_f32 v[128:129], v[128:129], v[18:19] op_sel_hi:[1,0]
	v_pk_mul_f32 v[154:155], v[126:127], v[18:19] op_sel_hi:[1,0]
	v_pk_mul_f32 v[158:159], v[124:125], v[18:19] op_sel_hi:[1,0]
	v_pk_mul_f32 v[124:125], v[122:123], v[18:19] op_sel_hi:[1,0]
	v_pk_mul_f32 v[126:127], v[120:121], v[18:19] op_sel_hi:[1,0]
	v_pk_mul_f32 v[156:157], v[118:119], v[18:19] op_sel_hi:[1,0]
	v_pk_mul_f32 v[160:161], v[116:117], v[18:19] op_sel_hi:[1,0]
	s_mov_b64 s[6:7], -1
	s_and_b64 vcc, exec, s[82:83]
	s_cbranch_vccz .LBB0_286
	v_mul_f32_e32 v173, v129, v129
	v_mul_f32_e32 v174, v131, v131
	v_mul_f32_e32 v175, v159, v159
	v_mul_f32_e32 v176, v155, v155
	s_and_b64 vcc, exec, s[84:85]
	v_ashrrev_i32_e32 v153, 31, v152
	v_fmac_f32_e32 v173, v128, v128
	v_fmac_f32_e32 v174, v130, v130
	v_fmac_f32_e32 v175, v158, v158
	v_fmac_f32_e32 v176, v154, v154
	s_cbranch_vccz .LBB0_282
	v_lshlrev_b64 v[120:121], 8, v[152:153]
	v_add_f32_e32 v18, v173, v174
	v_lshl_add_u64 v[120:121], s[18:19], 0, v[120:121]
	v_add_f32_e32 v18, v175, v18
	v_cvt_pk_bf16_f32 v116, v128, v129
	v_cvt_pk_bf16_f32 v117, v130, v131
	v_cvt_pk_bf16_f32 v118, v158, v159
	v_cvt_pk_bf16_f32 v119, v154, v155
	v_lshl_add_u64 v[120:121], v[146:147], 1, v[120:121]
	v_add_f32_e32 v18, v176, v18
	global_store_dwordx4 v[120:121], v[116:119], off
	s_nop 1
	v_mov_b32_e32 v116, v18
	s_nop 1
	v_permlane16_swap_b32_e32 v18, v116
	v_add_f32_e32 v18, v18, v116
	v_mov_b32_e32 v116, v18
	s_nop 1
	v_permlane32_swap_b32_e32 v18, v116
	s_and_saveexec_b64 s[6:7], s[8:9]
	s_cbranch_execz .LBB0_278
	v_lshl_add_u64 v[118:119], v[152:153], 4, s[34:35]
	v_add_f32_e32 v18, v18, v116
	global_store_dword v[118:119], v18, off

; __device__ __forceinline__ u32x4 pack8(const f32x4& v0, const f32x4& v1) { u32x4 w; w.x = cvt_pk_bf16(v0[0], v0[1]); w.y = cvt_pk_bf16(v0[2], v0[3]); w.z = cvt_pk_bf16(v1[0], v1[1]); w.w = cvt_pk_bf16(v1[2], v1[3]); return w; }
; __device__ __forceinline__ float sumsq8(const f32x4& a, const f32x4& b) { return (a[0] * a[0] + a[1] * a[1]) + (a[2] * a[2] + a[3] * a[3]) + (b[0] * b[0] + b[1] * b[1]) + (b[2] * b[2] + b[3] * b[3]); }
;     __device__ __forceinline__ void operator()(const f32x4 (&acc)[2][2][4][2], const Unit& u, int wr, int wc, int fr, int fq) const {
;     ...
;             for (int m = 0; m < 4; ++m) {
;                 int row_ = row0 + ai * 128 + m * 16; asm volatile("" : "+v"(row_)); const int row = row_;
;                 const float rstd = rs[wr * 64 + ai * 128 + m * 16 + fr];
;                 f32x4 v[2][2];
; #pragma unroll
;                 for (int bj = 0; bj < 2; ++bj) { v[bj][0] = acc[ai][bj][m][0] * rstd; v[bj][1] = acc[ai][bj][m][1] * rstd; }
;                 if (u.pn < 27) {
;                     bf16_t* dst = P + (size_t)row * LDP + u.pn * 256 + cw;
;                     *(u32x4*)(dst) = pack8(v[0][0], v[0][1]); *(u32x4*)(dst + 128) = pack8(v[1][0], v[1][1]);
;                 } else if (u.pn == 27) {
;                     bf16_t* dst = CQ + (size_t)row * 256 + cw;
;                     *(u32x4*)(dst) = pack8(v[0][0], v[0][1]); *(u32x4*)(dst + 128) = pack8(v[1][0], v[1][1]);
;                     const float s = quad_sum(sumsq8(v[0][0], v[0][1]) + sumsq8(v[1][0], v[1][1]));
;                     if (fq == 0) SSQQ[(size_t)row * 4 + wc] = s;
;                 } else {
;                     *(u32x4*)(CKV + (size_t)row * 128 + cw) = pack8(v[0][0], v[0][1]);
;                     const float s = quad_sum(sumsq8(v[0][0], v[0][1]));
;                     if (fq == 0) SSQKV[(size_t)row * 4 + wc] = s;
.LBB0_288:
	s_nop 1
	v_or_b32_e32 v116, 16, v171
	v_mov_b32_e32 v18, v232
	s_mov_b64 s[86:87], -1
	s_andn2_b64 vcc, exec, s[82:83]
	s_waitcnt lgkmcnt(0)
	v_pk_mul_f32 v[114:115], v[114:115], v[18:19] op_sel_hi:[1,0]
	v_pk_mul_f32 v[112:113], v[112:113], v[18:19] op_sel_hi:[1,0]
	v_pk_mul_f32 v[118:119], v[110:111], v[18:19] op_sel_hi:[1,0]
	v_pk_mul_f32 v[122:123], v[108:109], v[18:19] op_sel_hi:[1,0]
	v_pk_mul_f32 v[108:109], v[106:107], v[18:19] op_sel_hi:[1,0]
	v_pk_mul_f32 v[110:111], v[104:105], v[18:19] op_sel_hi:[1,0]
	v_pk_mul_f32 v[120:121], v[102:103], v[18:19] op_sel_hi:[1,0]
	v_pk_mul_f32 v[124:125], v[100:101], v[18:19] op_sel_hi:[1,0]
	v_cndmask_b32_e64 v18, 0, 1, s[82:83]
	v_cmp_ne_u32_e64 s[6:7], 1, v18
	v_cndmask_b32_e64 v18, 0, 1, s[84:85]
	v_cmp_ne_u32_e64 s[4:5], 1, v18
	s_cbranch_vccnz .LBB0_301
	v_mul_f32_e32 v154, v113, v113
	v_mul_f32_e32 v155, v115, v115
	v_mul_f32_e32 v156, v123, v123
	v_mul_f32_e32 v157, v119, v119
	s_mov_b64 s[82:83], -1
	s_and_b64 vcc, exec, s[4:5]
	v_ashrrev_i32_e32 v117, 31, v116
	v_fmac_f32_e32 v154, v112, v112
	v_fmac_f32_e32 v155, v114, v114
	v_fmac_f32_e32 v156, v122, v122
	v_fmac_f32_e32 v157, v118, v118
	s_cbranch_vccnz .LBB0_296
	v_lshlrev_b64 v[104:105], 8, v[116:117]
	v_add_f32_e32 v18, v154, v155
	v_lshl_add_u64 v[104:105], s[18:19], 0, v[104:105]
	v_add_f32_e32 v18, v156, v18
	v_cvt_pk_bf16_f32 v100, v112, v113
	v_cvt_pk_bf16_f32 v101, v114, v115
	v_cvt_pk_bf16_f32 v102, v122, v123
	v_cvt_pk_bf16_f32 v103, v118, v119
	v_lshl_add_u64 v[104:105], v[146:147], 1, v[104:105]
	v_add_f32_e32 v18, v157, v18
	global_store_dwordx4 v[104:105], v[100:103], off
	s_nop 1
	v_mov_b32_e32 v100, v18
	s_nop 1
	v_permlane16_swap_b32_e32 v18, v100
	v_add_f32_e32 v18, v18, v100
	v_mov_b32_e32 v100, v18
	s_nop 1
	v_permlane32_swap_b32_e32 v18, v100
	s_and_saveexec_b64 s[82:83], s[8:9]
	s_cbranch_execz .LBB0_292
	v_lshl_add_u64 v[102:103], v[116:117], 4, s[34:35]
	v_add_f32_e32 v18, v18, v100
	global_store_dword v[102:103], v18, off

; __device__ __forceinline__ u32x4 pack8(const f32x4& v0, const f32x4& v1) { u32x4 w; w.x = cvt_pk_bf16(v0[0], v0[1]); w.y = cvt_pk_bf16(v0[2], v0[3]); w.z = cvt_pk_bf16(v1[0], v1[1]); w.w = cvt_pk_bf16(v1[2], v1[3]); return w; }
; __device__ __forceinline__ float sumsq8(const f32x4& a, const f32x4& b) { return (a[0] * a[0] + a[1] * a[1]) + (a[2] * a[2] + a[3] * a[3]) + (b[0] * b[0] + b[1] * b[1]) + (b[2] * b[2] + b[3] * b[3]); }
;     __device__ __forceinline__ void operator()(const f32x4 (&acc)[2][2][4][2], const Unit& u, int wr, int wc, int fr, int fq) const {
;     ...
;             for (int m = 0; m < 4; ++m) {
;                 int row_ = row0 + ai * 128 + m * 16; asm volatile("" : "+v"(row_)); const int row = row_;
;                 const float rstd = rs[wr * 64 + ai * 128 + m * 16 + fr];
;                 f32x4 v[2][2];
; #pragma unroll
;                 for (int bj = 0; bj < 2; ++bj) { v[bj][0] = acc[ai][bj][m][0] * rstd; v[bj][1] = acc[ai][bj][m][1] * rstd; }
;                 if (u.pn < 27) {
;                     bf16_t* dst = P + (size_t)row * LDP + u.pn * 256 + cw;
;                     *(u32x4*)(dst) = pack8(v[0][0], v[0][1]); *(u32x4*)(dst + 128) = pack8(v[1][0], v[1][1]);
;                 } else if (u.pn == 27) {
;                     bf16_t* dst = CQ + (size_t)row * 256 + cw;
;                     *(u32x4*)(dst) = pack8(v[0][0], v[0][1]); *(u32x4*)(dst + 128) = pack8(v[1][0], v[1][1]);
;                     const float s = quad_sum(sumsq8(v[0][0], v[0][1]) + sumsq8(v[1][0], v[1][1]));
;                     if (fq == 0) SSQQ[(size_t)row * 4 + wc] = s;
;                 } else {
;                     *(u32x4*)(CKV + (size_t)row * 128 + cw) = pack8(v[0][0], v[0][1]);
;                     const float s = quad_sum(sumsq8(v[0][0], v[0][1]));
;                     if (fq == 0) SSQKV[(size_t)row * 4 + wc] = s;
.LBB0_303:
	s_nop 1
	v_or_b32_e32 v100, 32, v171
	v_mov_b32_e32 v18, v233
	s_and_b64 vcc, exec, s[6:7]
	s_mov_b64 s[82:83], -1
	s_waitcnt lgkmcnt(0)
	v_pk_mul_f32 v[98:99], v[98:99], v[18:19] op_sel_hi:[1,0]
	v_pk_mul_f32 v[96:97], v[96:97], v[18:19] op_sel_hi:[1,0]
	v_pk_mul_f32 v[102:103], v[94:95], v[18:19] op_sel_hi:[1,0]
	v_pk_mul_f32 v[106:107], v[92:93], v[18:19] op_sel_hi:[1,0]
	v_pk_mul_f32 v[92:93], v[90:91], v[18:19] op_sel_hi:[1,0]
	v_pk_mul_f32 v[94:95], v[88:89], v[18:19] op_sel_hi:[1,0]
	v_pk_mul_f32 v[104:105], v[86:87], v[18:19] op_sel_hi:[1,0]
	v_pk_mul_f32 v[108:109], v[84:85], v[18:19] op_sel_hi:[1,0]
	s_cbranch_vccnz .LBB0_316
	v_mul_f32_e32 v118, v97, v97
	v_mul_f32_e32 v119, v99, v99
	v_mul_f32_e32 v120, v107, v107
	v_mul_f32_e32 v121, v103, v103
	s_and_b64 vcc, exec, s[4:5]
	v_ashrrev_i32_e32 v101, 31, v100
	v_fmac_f32_e32 v118, v96, v96
	v_fmac_f32_e32 v119, v98, v98
	v_fmac_f32_e32 v120, v106, v106
	v_fmac_f32_e32 v121, v102, v102
	s_cbranch_vccnz .LBB0_311
	v_lshlrev_b64 v[88:89], 8, v[100:101]
	v_add_f32_e32 v18, v118, v119
	v_lshl_add_u64 v[88:89], s[18:19], 0, v[88:89]
	v_add_f32_e32 v18, v120, v18
	v_cvt_pk_bf16_f32 v84, v96, v97
	v_cvt_pk_bf16_f32 v85, v98, v99
	v_cvt_pk_bf16_f32 v86, v106, v107
	v_cvt_pk_bf16_f32 v87, v102, v103
	v_lshl_add_u64 v[88:89], v[146:147], 1, v[88:89]
	v_add_f32_e32 v18, v121, v18
	global_store_dwordx4 v[88:89], v[84:87], off
	s_nop 1
	v_mov_b32_e32 v84, v18
	s_nop 1
	v_permlane16_swap_b32_e32 v18, v84
	v_add_f32_e32 v18, v18, v84
	v_mov_b32_e32 v84, v18
	s_nop 1
	v_permlane32_swap_b32_e32 v18, v84
	s_and_saveexec_b64 s[82:83], s[8:9]
	s_cbranch_execz .LBB0_307
	v_lshl_add_u64 v[86:87], v[100:101], 4, s[34:35]
	v_add_f32_e32 v18, v18, v84
	global_store_dword v[86:87], v18, off

; __device__ __forceinline__ u32x4 pack8(const f32x4& v0, const f32x4& v1) { u32x4 w; w.x = cvt_pk_bf16(v0[0], v0[1]); w.y = cvt_pk_bf16(v0[2], v0[3]); w.z = cvt_pk_bf16(v1[0], v1[1]); w.w = cvt_pk_bf16(v1[2], v1[3]); return w; }
; __device__ __forceinline__ float sumsq8(const f32x4& a, const f32x4& b) { return (a[0] * a[0] + a[1] * a[1]) + (a[2] * a[2] + a[3] * a[3]) + (b[0] * b[0] + b[1] * b[1]) + (b[2] * b[2] + b[3] * b[3]); }
;     __device__ __forceinline__ void operator()(const f32x4 (&acc)[2][2][4][2], const Unit& u, int wr, int wc, int fr, int fq) const {
;     ...
;             for (int m = 0; m < 4; ++m) {
;                 int row_ = row0 + ai * 128 + m * 16; asm volatile("" : "+v"(row_)); const int row = row_;
;                 const float rstd = rs[wr * 64 + ai * 128 + m * 16 + fr];
;                 f32x4 v[2][2];
; #pragma unroll
;                 for (int bj = 0; bj < 2; ++bj) { v[bj][0] = acc[ai][bj][m][0] * rstd; v[bj][1] = acc[ai][bj][m][1] * rstd; }
;                 if (u.pn < 27) {
;                     bf16_t* dst = P + (size_t)row * LDP + u.pn * 256 + cw;
;                     *(u32x4*)(dst) = pack8(v[0][0], v[0][1]); *(u32x4*)(dst + 128) = pack8(v[1][0], v[1][1]);
;                 } else if (u.pn == 27) {
;                     bf16_t* dst = CQ + (size_t)row * 256 + cw;
;                     *(u32x4*)(dst) = pack8(v[0][0], v[0][1]); *(u32x4*)(dst + 128) = pack8(v[1][0], v[1][1]);
;                     const float s = quad_sum(sumsq8(v[0][0], v[0][1]) + sumsq8(v[1][0], v[1][1]));
;                     if (fq == 0) SSQQ[(size_t)row * 4 + wc] = s;
;                 } else {
;                     *(u32x4*)(CKV + (size_t)row * 128 + cw) = pack8(v[0][0], v[0][1]);
;                     const float s = quad_sum(sumsq8(v[0][0], v[0][1]));
;                     if (fq == 0) SSQKV[(size_t)row * 4 + wc] = s;
.LBB0_318:
	s_nop 1
	v_or_b32_e32 v84, 48, v171
	v_mov_b32_e32 v18, v234
	s_and_b64 vcc, exec, s[6:7]
	s_mov_b64 s[82:83], -1
	s_waitcnt lgkmcnt(0)
	v_pk_mul_f32 v[82:83], v[82:83], v[18:19] op_sel_hi:[1,0]
	v_pk_mul_f32 v[80:81], v[80:81], v[18:19] op_sel_hi:[1,0]
	v_pk_mul_f32 v[86:87], v[78:79], v[18:19] op_sel_hi:[1,0]
	v_pk_mul_f32 v[90:91], v[76:77], v[18:19] op_sel_hi:[1,0]
	v_pk_mul_f32 v[76:77], v[74:75], v[18:19] op_sel_hi:[1,0]
	v_pk_mul_f32 v[78:79], v[72:73], v[18:19] op_sel_hi:[1,0]
	v_pk_mul_f32 v[88:89], v[70:71], v[18:19] op_sel_hi:[1,0]
	v_pk_mul_f32 v[92:93], v[68:69], v[18:19] op_sel_hi:[1,0]
	s_cbranch_vccnz .LBB0_331
	v_mul_f32_e32 v102, v81, v81
	v_mul_f32_e32 v103, v83, v83
	v_mul_f32_e32 v104, v91, v91
	v_mul_f32_e32 v105, v87, v87
	s_and_b64 vcc, exec, s[4:5]
	v_ashrrev_i32_e32 v85, 31, v84
	v_fmac_f32_e32 v102, v80, v80
	v_fmac_f32_e32 v103, v82, v82
	v_fmac_f32_e32 v104, v90, v90
	v_fmac_f32_e32 v105, v86, v86
	s_cbranch_vccnz .LBB0_326
	v_lshlrev_b64 v[72:73], 8, v[84:85]
	v_add_f32_e32 v18, v102, v103
	v_lshl_add_u64 v[72:73], s[18:19], 0, v[72:73]
	v_add_f32_e32 v18, v104, v18
	v_cvt_pk_bf16_f32 v68, v80, v81
	v_cvt_pk_bf16_f32 v69, v82, v83
	v_cvt_pk_bf16_f32 v70, v90, v91
	v_cvt_pk_bf16_f32 v71, v86, v87
	v_lshl_add_u64 v[72:73], v[146:147], 1, v[72:73]
	v_add_f32_e32 v18, v105, v18
	global_store_dwordx4 v[72:73], v[68:71], off
	s_nop 1
	v_mov_b32_e32 v68, v18
	s_nop 1
	v_permlane16_swap_b32_e32 v18, v68
	v_add_f32_e32 v18, v18, v68
	v_mov_b32_e32 v68, v18
	s_nop 1
	v_permlane32_swap_b32_e32 v18, v68
	s_and_saveexec_b64 s[82:83], s[8:9]
	s_cbranch_execz .LBB0_322
	v_lshl_add_u64 v[70:71], v[84:85], 4, s[34:35]
	v_add_f32_e32 v18, v18, v68
	global_store_dword v[70:71], v18, off

; __device__ __forceinline__ u32x4 pack8(const f32x4& v0, const f32x4& v1) { u32x4 w; w.x = cvt_pk_bf16(v0[0], v0[1]); w.y = cvt_pk_bf16(v0[2], v0[3]); w.z = cvt_pk_bf16(v1[0], v1[1]); w.w = cvt_pk_bf16(v1[2], v1[3]); return w; }
; __device__ __forceinline__ float sumsq8(const f32x4& a, const f32x4& b) { return (a[0] * a[0] + a[1] * a[1]) + (a[2] * a[2] + a[3] * a[3]) + (b[0] * b[0] + b[1] * b[1]) + (b[2] * b[2] + b[3] * b[3]); }
;     __device__ __forceinline__ void operator()(const f32x4 (&acc)[2][2][4][2], const Unit& u, int wr, int wc, int fr, int fq) const {
;     ...
;             for (int m = 0; m < 4; ++m) {
;                 int row_ = row0 + ai * 128 + m * 16; asm volatile("" : "+v"(row_)); const int row = row_;
;                 const float rstd = rs[wr * 64 + ai * 128 + m * 16 + fr];
;                 f32x4 v[2][2];
; #pragma unroll
;                 for (int bj = 0; bj < 2; ++bj) { v[bj][0] = acc[ai][bj][m][0] * rstd; v[bj][1] = acc[ai][bj][m][1] * rstd; }
;                 if (u.pn < 27) {
;                     bf16_t* dst = P + (size_t)row * LDP + u.pn * 256 + cw;
;                     *(u32x4*)(dst) = pack8(v[0][0], v[0][1]); *(u32x4*)(dst + 128) = pack8(v[1][0], v[1][1]);
;                 } else if (u.pn == 27) {
;                     bf16_t* dst = CQ + (size_t)row * 256 + cw;
;                     *(u32x4*)(dst) = pack8(v[0][0], v[0][1]); *(u32x4*)(dst + 128) = pack8(v[1][0], v[1][1]);
;                     const float s = quad_sum(sumsq8(v[0][0], v[0][1]) + sumsq8(v[1][0], v[1][1]));
;                     if (fq == 0) SSQQ[(size_t)row * 4 + wc] = s;
;                 } else {
;                     *(u32x4*)(CKV + (size_t)row * 128 + cw) = pack8(v[0][0], v[0][1]);
;                     const float s = quad_sum(sumsq8(v[0][0], v[0][1]));
;                     if (fq == 0) SSQKV[(size_t)row * 4 + wc] = s;
.LBB0_333:
	s_nop 1
	v_add_u32_e32 v68, 0x80, v171
	v_mov_b32_e32 v18, v235
	s_and_b64 vcc, exec, s[6:7]
	s_mov_b64 s[82:83], -1
	s_waitcnt lgkmcnt(0)
	v_pk_mul_f32 v[66:67], v[66:67], v[18:19] op_sel_hi:[1,0]
	v_pk_mul_f32 v[64:65], v[64:65], v[18:19] op_sel_hi:[1,0]
	v_pk_mul_f32 v[70:71], v[62:63], v[18:19] op_sel_hi:[1,0]
	v_pk_mul_f32 v[74:75], v[60:61], v[18:19] op_sel_hi:[1,0]
	v_pk_mul_f32 v[60:61], v[58:59], v[18:19] op_sel_hi:[1,0]
	v_pk_mul_f32 v[62:63], v[56:57], v[18:19] op_sel_hi:[1,0]
	v_pk_mul_f32 v[72:73], v[54:55], v[18:19] op_sel_hi:[1,0]
	v_pk_mul_f32 v[76:77], v[52:53], v[18:19] op_sel_hi:[1,0]
	s_cbranch_vccnz .LBB0_346
	v_mul_f32_e32 v86, v65, v65
	v_mul_f32_e32 v87, v67, v67
	v_mul_f32_e32 v88, v75, v75
	v_mul_f32_e32 v89, v71, v71
	s_and_b64 vcc, exec, s[4:5]
	v_ashrrev_i32_e32 v69, 31, v68
	v_fmac_f32_e32 v86, v64, v64
	v_fmac_f32_e32 v87, v66, v66
	v_fmac_f32_e32 v88, v74, v74
	v_fmac_f32_e32 v89, v70, v70
	s_cbranch_vccnz .LBB0_341
	v_lshlrev_b64 v[56:57], 8, v[68:69]
	v_add_f32_e32 v18, v86, v87
	v_lshl_add_u64 v[56:57], s[18:19], 0, v[56:57]
	v_add_f32_e32 v18, v88, v18
	v_cvt_pk_bf16_f32 v52, v64, v65
	v_cvt_pk_bf16_f32 v53, v66, v67
	v_cvt_pk_bf16_f32 v54, v74, v75
	v_cvt_pk_bf16_f32 v55, v70, v71
	v_lshl_add_u64 v[56:57], v[146:147], 1, v[56:57]
	v_add_f32_e32 v18, v89, v18
	global_store_dwordx4 v[56:57], v[52:55], off
	s_nop 1
	v_mov_b32_e32 v52, v18
	s_nop 1
	v_permlane16_swap_b32_e32 v18, v52
	v_add_f32_e32 v18, v18, v52
	v_mov_b32_e32 v52, v18
	s_nop 1
	v_permlane32_swap_b32_e32 v18, v52
	s_and_saveexec_b64 s[82:83], s[8:9]
	s_cbranch_execz .LBB0_337
	v_lshl_add_u64 v[54:55], v[68:69], 4, s[34:35]
	v_add_f32_e32 v18, v18, v52
	global_store_dword v[54:55], v18, off

; __device__ __forceinline__ u32x4 pack8(const f32x4& v0, const f32x4& v1) { u32x4 w; w.x = cvt_pk_bf16(v0[0], v0[1]); w.y = cvt_pk_bf16(v0[2], v0[3]); w.z = cvt_pk_bf16(v1[0], v1[1]); w.w = cvt_pk_bf16(v1[2], v1[3]); return w; }
; __device__ __forceinline__ float sumsq8(const f32x4& a, const f32x4& b) { return (a[0] * a[0] + a[1] * a[1]) + (a[2] * a[2] + a[3] * a[3]) + (b[0] * b[0] + b[1] * b[1]) + (b[2] * b[2] + b[3] * b[3]); }
;     __device__ __forceinline__ void operator()(const f32x4 (&acc)[2][2][4][2], const Unit& u, int wr, int wc, int fr, int fq) const {
;     ...
;             for (int m = 0; m < 4; ++m) {
;                 int row_ = row0 + ai * 128 + m * 16; asm volatile("" : "+v"(row_)); const int row = row_;
;                 const float rstd = rs[wr * 64 + ai * 128 + m * 16 + fr];
;                 f32x4 v[2][2];
; #pragma unroll
;                 for (int bj = 0; bj < 2; ++bj) { v[bj][0] = acc[ai][bj][m][0] * rstd; v[bj][1] = acc[ai][bj][m][1] * rstd; }
;                 if (u.pn < 27) {
;                     bf16_t* dst = P + (size_t)row * LDP + u.pn * 256 + cw;
;                     *(u32x4*)(dst) = pack8(v[0][0], v[0][1]); *(u32x4*)(dst + 128) = pack8(v[1][0], v[1][1]);
;                 } else if (u.pn == 27) {
;                     bf16_t* dst = CQ + (size_t)row * 256 + cw;
;                     *(u32x4*)(dst) = pack8(v[0][0], v[0][1]); *(u32x4*)(dst + 128) = pack8(v[1][0], v[1][1]);
;                     const float s = quad_sum(sumsq8(v[0][0], v[0][1]) + sumsq8(v[1][0], v[1][1]));
;                     if (fq == 0) SSQQ[(size_t)row * 4 + wc] = s;
;                 } else {
;                     *(u32x4*)(CKV + (size_t)row * 128 + cw) = pack8(v[0][0], v[0][1]);
;                     const float s = quad_sum(sumsq8(v[0][0], v[0][1]));
;                     if (fq == 0) SSQKV[(size_t)row * 4 + wc] = s;
.LBB0_348:
	s_nop 1
	v_add_u32_e32 v52, 0x90, v171
	v_mov_b32_e32 v18, v236
	s_and_b64 vcc, exec, s[6:7]
	s_mov_b64 s[82:83], -1
	s_waitcnt lgkmcnt(0)
	v_pk_mul_f32 v[50:51], v[50:51], v[18:19] op_sel_hi:[1,0]
	v_pk_mul_f32 v[48:49], v[48:49], v[18:19] op_sel_hi:[1,0]
	v_pk_mul_f32 v[54:55], v[46:47], v[18:19] op_sel_hi:[1,0]
	v_pk_mul_f32 v[58:59], v[44:45], v[18:19] op_sel_hi:[1,0]
	v_pk_mul_f32 v[44:45], v[42:43], v[18:19] op_sel_hi:[1,0]
	v_pk_mul_f32 v[46:47], v[40:41], v[18:19] op_sel_hi:[1,0]
	v_pk_mul_f32 v[56:57], v[38:39], v[18:19] op_sel_hi:[1,0]
	v_pk_mul_f32 v[60:61], v[36:37], v[18:19] op_sel_hi:[1,0]
	s_cbranch_vccnz .LBB0_361
	v_mul_f32_e32 v70, v49, v49
	v_mul_f32_e32 v71, v51, v51
	v_mul_f32_e32 v72, v59, v59
	v_mul_f32_e32 v73, v55, v55
	s_and_b64 vcc, exec, s[4:5]
	v_ashrrev_i32_e32 v53, 31, v52
	v_fmac_f32_e32 v70, v48, v48
	v_fmac_f32_e32 v71, v50, v50
	v_fmac_f32_e32 v72, v58, v58
	v_fmac_f32_e32 v73, v54, v54
	s_cbranch_vccnz .LBB0_356
	v_lshlrev_b64 v[40:41], 8, v[52:53]
	v_add_f32_e32 v18, v70, v71
	v_lshl_add_u64 v[40:41], s[18:19], 0, v[40:41]
	v_add_f32_e32 v18, v72, v18
	v_cvt_pk_bf16_f32 v36, v48, v49
	v_cvt_pk_bf16_f32 v37, v50, v51
	v_cvt_pk_bf16_f32 v38, v58, v59
	v_cvt_pk_bf16_f32 v39, v54, v55
	v_lshl_add_u64 v[40:41], v[146:147], 1, v[40:41]
	v_add_f32_e32 v18, v73, v18
	global_store_dwordx4 v[40:41], v[36:39], off
	s_nop 1
	v_mov_b32_e32 v36, v18
	s_nop 1
	v_permlane16_swap_b32_e32 v18, v36
	v_add_f32_e32 v18, v18, v36
	v_mov_b32_e32 v36, v18
	s_nop 1
	v_permlane32_swap_b32_e32 v18, v36
	s_and_saveexec_b64 s[82:83], s[8:9]
	s_cbranch_execz .LBB0_352
	v_lshl_add_u64 v[38:39], v[52:53], 4, s[34:35]
	v_add_f32_e32 v18, v18, v36
	global_store_dword v[38:39], v18, off

; __device__ __forceinline__ u32x4 pack8(const f32x4& v0, const f32x4& v1) { u32x4 w; w.x = cvt_pk_bf16(v0[0], v0[1]); w.y = cvt_pk_bf16(v0[2], v0[3]); w.z = cvt_pk_bf16(v1[0], v1[1]); w.w = cvt_pk_bf16(v1[2], v1[3]); return w; }
; __device__ __forceinline__ float sumsq8(const f32x4& a, const f32x4& b) { return (a[0] * a[0] + a[1] * a[1]) + (a[2] * a[2] + a[3] * a[3]) + (b[0] * b[0] + b[1] * b[1]) + (b[2] * b[2] + b[3] * b[3]); }
;     __device__ __forceinline__ void operator()(const f32x4 (&acc)[2][2][4][2], const Unit& u, int wr, int wc, int fr, int fq) const {
;     ...
;             for (int m = 0; m < 4; ++m) {
;                 int row_ = row0 + ai * 128 + m * 16; asm volatile("" : "+v"(row_)); const int row = row_;
;                 const float rstd = rs[wr * 64 + ai * 128 + m * 16 + fr];
;                 f32x4 v[2][2];
; #pragma unroll
;                 for (int bj = 0; bj < 2; ++bj) { v[bj][0] = acc[ai][bj][m][0] * rstd; v[bj][1] = acc[ai][bj][m][1] * rstd; }
;                 if (u.pn < 27) {
;                     bf16_t* dst = P + (size_t)row * LDP + u.pn * 256 + cw;
;                     *(u32x4*)(dst) = pack8(v[0][0], v[0][1]); *(u32x4*)(dst + 128) = pack8(v[1][0], v[1][1]);
;                 } else if (u.pn == 27) {
;                     bf16_t* dst = CQ + (size_t)row * 256 + cw;
;                     *(u32x4*)(dst) = pack8(v[0][0], v[0][1]); *(u32x4*)(dst + 128) = pack8(v[1][0], v[1][1]);
;                     const float s = quad_sum(sumsq8(v[0][0], v[0][1]) + sumsq8(v[1][0], v[1][1]));
;                     if (fq == 0) SSQQ[(size_t)row * 4 + wc] = s;
;                 } else {
;                     *(u32x4*)(CKV + (size_t)row * 128 + cw) = pack8(v[0][0], v[0][1]);
;                     const float s = quad_sum(sumsq8(v[0][0], v[0][1]));
;                     if (fq == 0) SSQKV[(size_t)row * 4 + wc] = s;
.LBB0_363:
	s_nop 1
	v_add_u32_e32 v36, 0xa0, v171
	v_mov_b32_e32 v18, v237
	s_and_b64 vcc, exec, s[6:7]
	s_mov_b64 s[82:83], -1
	s_waitcnt lgkmcnt(0)
	v_pk_mul_f32 v[34:35], v[34:35], v[18:19] op_sel_hi:[1,0]
	v_pk_mul_f32 v[32:33], v[32:33], v[18:19] op_sel_hi:[1,0]
	v_pk_mul_f32 v[38:39], v[30:31], v[18:19] op_sel_hi:[1,0]
	v_pk_mul_f32 v[42:43], v[28:29], v[18:19] op_sel_hi:[1,0]
	v_pk_mul_f32 v[28:29], v[26:27], v[18:19] op_sel_hi:[1,0]
	v_pk_mul_f32 v[30:31], v[24:25], v[18:19] op_sel_hi:[1,0]
	v_pk_mul_f32 v[40:41], v[22:23], v[18:19] op_sel_hi:[1,0]
	v_pk_mul_f32 v[44:45], v[20:21], v[18:19] op_sel_hi:[1,0]
	s_cbranch_vccnz .LBB0_376
	v_mul_f32_e32 v54, v33, v33
	v_mul_f32_e32 v55, v35, v35
	v_mul_f32_e32 v56, v43, v43
	v_mul_f32_e32 v57, v39, v39
	s_and_b64 vcc, exec, s[4:5]
	v_ashrrev_i32_e32 v37, 31, v36
	v_fmac_f32_e32 v54, v32, v32
	v_fmac_f32_e32 v55, v34, v34
	v_fmac_f32_e32 v56, v42, v42
	v_fmac_f32_e32 v57, v38, v38
	s_cbranch_vccnz .LBB0_371
	v_lshlrev_b64 v[24:25], 8, v[36:37]
	v_add_f32_e32 v18, v54, v55
	v_lshl_add_u64 v[24:25], s[18:19], 0, v[24:25]
	v_add_f32_e32 v18, v56, v18
	v_cvt_pk_bf16_f32 v20, v32, v33
	v_cvt_pk_bf16_f32 v21, v34, v35
	v_cvt_pk_bf16_f32 v22, v42, v43
	v_cvt_pk_bf16_f32 v23, v38, v39
	v_lshl_add_u64 v[24:25], v[146:147], 1, v[24:25]
	v_add_f32_e32 v18, v57, v18
	global_store_dwordx4 v[24:25], v[20:23], off
	s_nop 1
	v_mov_b32_e32 v20, v18
	s_nop 1
	v_permlane16_swap_b32_e32 v18, v20
	v_add_f32_e32 v18, v18, v20
	v_mov_b32_e32 v20, v18
	s_nop 1
	v_permlane32_swap_b32_e32 v18, v20
	s_and_saveexec_b64 s[82:83], s[8:9]
	s_cbranch_execz .LBB0_367
	v_lshl_add_u64 v[22:23], v[36:37], 4, s[34:35]
	v_add_f32_e32 v18, v18, v20
	global_store_dword v[22:23], v18, off

; __device__ __forceinline__ u32x4 pack8(const f32x4& v0, const f32x4& v1) { u32x4 w; w.x = cvt_pk_bf16(v0[0], v0[1]); w.y = cvt_pk_bf16(v0[2], v0[3]); w.z = cvt_pk_bf16(v1[0], v1[1]); w.w = cvt_pk_bf16(v1[2], v1[3]); return w; }
; __device__ __forceinline__ float sumsq8(const f32x4& a, const f32x4& b) { return (a[0] * a[0] + a[1] * a[1]) + (a[2] * a[2] + a[3] * a[3]) + (b[0] * b[0] + b[1] * b[1]) + (b[2] * b[2] + b[3] * b[3]); }
;     __device__ __forceinline__ void operator()(const f32x4 (&acc)[2][2][4][2], const Unit& u, int wr, int wc, int fr, int fq) const {
;     ...
;             for (int m = 0; m < 4; ++m) {
;                 int row_ = row0 + ai * 128 + m * 16; asm volatile("" : "+v"(row_)); const int row = row_;
;                 const float rstd = rs[wr * 64 + ai * 128 + m * 16 + fr];
;                 f32x4 v[2][2];
; #pragma unroll
;                 for (int bj = 0; bj < 2; ++bj) { v[bj][0] = acc[ai][bj][m][0] * rstd; v[bj][1] = acc[ai][bj][m][1] * rstd; }
;                 if (u.pn < 27) {
;                     bf16_t* dst = P + (size_t)row * LDP + u.pn * 256 + cw;
;                     *(u32x4*)(dst) = pack8(v[0][0], v[0][1]); *(u32x4*)(dst + 128) = pack8(v[1][0], v[1][1]);
;                 } else if (u.pn == 27) {
;                     bf16_t* dst = CQ + (size_t)row * 256 + cw;
;                     *(u32x4*)(dst) = pack8(v[0][0], v[0][1]); *(u32x4*)(dst + 128) = pack8(v[1][0], v[1][1]);
;                     const float s = quad_sum(sumsq8(v[0][0], v[0][1]) + sumsq8(v[1][0], v[1][1]));
;                     if (fq == 0) SSQQ[(size_t)row * 4 + wc] = s;
;                 } else {
;                     *(u32x4*)(CKV + (size_t)row * 128 + cw) = pack8(v[0][0], v[0][1]);
;                     const float s = quad_sum(sumsq8(v[0][0], v[0][1]));
;                     if (fq == 0) SSQKV[(size_t)row * 4 + wc] = s;
.LBB0_378:
	s_nop 1
	v_add_u32_e32 v20, 0xb0, v171
	v_mov_b32_e32 v18, v238
	s_and_b64 vcc, exec, s[6:7]
	s_mov_b64 s[6:7], -1
	s_waitcnt lgkmcnt(0)
	v_pk_mul_f32 v[16:17], v[16:17], v[18:19] op_sel_hi:[1,0]
	v_pk_mul_f32 v[14:15], v[14:15], v[18:19] op_sel_hi:[1,0]
	v_pk_mul_f32 v[22:23], v[12:13], v[18:19] op_sel_hi:[1,0]
	v_pk_mul_f32 v[26:27], v[10:11], v[18:19] op_sel_hi:[1,0]
	v_pk_mul_f32 v[10:11], v[8:9], v[18:19] op_sel_hi:[1,0]
	v_pk_mul_f32 v[12:13], v[6:7], v[18:19] op_sel_hi:[1,0]
	v_pk_mul_f32 v[24:25], v[4:5], v[18:19] op_sel_hi:[1,0]
	v_pk_mul_f32 v[28:29], v[2:3], v[18:19] op_sel_hi:[1,0]
	s_cbranch_vccnz .LBB0_392
	v_mul_f32_e32 v38, v15, v15
	v_mul_f32_e32 v39, v17, v17
	v_mul_f32_e32 v40, v27, v27
	v_mul_f32_e32 v41, v23, v23
	s_and_b64 vcc, exec, s[4:5]
	v_ashrrev_i32_e32 v21, 31, v20
	v_fmac_f32_e32 v38, v14, v14
	v_fmac_f32_e32 v39, v16, v16
	v_fmac_f32_e32 v40, v26, v26
	v_fmac_f32_e32 v41, v22, v22
	s_cbranch_vccnz .LBB0_386
	v_lshlrev_b64 v[6:7], 8, v[20:21]
	v_lshl_add_u64 v[6:7], s[18:19], 0, v[6:7]
	v_cvt_pk_bf16_f32 v2, v14, v15
	v_cvt_pk_bf16_f32 v3, v16, v17
	v_cvt_pk_bf16_f32 v4, v26, v27
	v_cvt_pk_bf16_f32 v5, v22, v23
	v_lshl_add_u64 v[6:7], v[146:147], 1, v[6:7]
	global_store_dwordx4 v[6:7], v[2:5], off
	s_nop 1
	v_add_f32_e32 v2, v38, v39
	v_add_f32_e32 v2, v40, v2
	v_add_f32_e32 v2, v41, v2
	v_mov_b32_e32 v3, v2
	s_nop 1
	v_permlane16_swap_b32_e32 v2, v3
	v_add_f32_e32 v2, v2, v3
	v_mov_b32_e32 v3, v2
	s_nop 1
	v_permlane32_swap_b32_e32 v2, v3
	s_and_saveexec_b64 s[4:5], s[8:9]
	s_cbranch_execz .LBB0_382
	v_lshl_add_u64 v[4:5], v[20:21], 4, s[34:35]
	v_add_f32_e32 v2, v2, v3
	global_store_dword v[4:5], v2, off
